# grid barrier: the last-arriving XCD leader bumps every per-XCD release word itself; waiters poll their own XCD's word (pollers stay spread over 8 addresses); on top of the G2 load hoist
# baseline (speedup 1.0000x reference)
.LBB0_403:
	s_or_b64 exec, exec, s[14:15]
	s_waitcnt vmcnt(0)
	v_readfirstlane_b32 s12, v3
	v_sub_u32_e32 v4, 0, v2
	s_mov_b64 s[16:17], -1
	v_add_u32_e32 v3, s12, v0
	v_cvt_f32_u32_e32 v0, v2
	s_add_u32 s12, s8, 0xf104500
	s_addc_u32 s13, s9, 0
	v_rcp_iflag_f32_e32 v0, v0
	s_nop 0
	v_mul_f32_e32 v0, 0x4f7ffffe, v0
	v_cvt_u32_f32_e32 v0, v0
	v_mul_lo_u32 v4, v4, v0
	v_mul_hi_u32 v4, v0, v4
	v_add_u32_e32 v0, v0, v4
	v_mul_hi_u32 v0, v3, v0
	v_mul_lo_u32 v4, v0, v2
	v_sub_u32_e32 v4, v3, v4
	v_cmp_ge_u32_e32 vcc, v4, v2
	v_add_u32_e32 v5, 1, v0
	v_add_u32_e32 v3, 1, v3
	v_cndmask_b32_e32 v0, v0, v5, vcc
	v_sub_u32_e32 v5, v4, v2
	v_cndmask_b32_e32 v4, v4, v5, vcc
	v_cmp_ge_u32_e32 vcc, v4, v2
	v_add_u32_e32 v4, 1, v0
	s_nop 0
	v_cndmask_b32_e32 v0, v0, v4, vcc
	v_mul_lo_u32 v4, v2, v0
	v_add_u32_e32 v2, v4, v2
	v_cmp_ne_u32_e32 vcc, v3, v2
	v_mov_b64_e32 v[2:3], s[12:13]
	s_cbranch_vccnz .Lxg_5
	v_mov_b32_e32 v4, 0xf103400
	global_atomic_add v4, v247, s[8:9] offset:0
	global_atomic_add v4, v247, s[8:9] offset:256
	global_atomic_add v4, v247, s[8:9] offset:512
	global_atomic_add v4, v247, s[8:9] offset:768
	global_atomic_add v4, v247, s[8:9] offset:1024
	global_atomic_add v4, v247, s[8:9] offset:1280
	global_atomic_add v4, v247, s[8:9] offset:1536
	global_atomic_add v4, v247, s[8:9] offset:1792
	global_atomic_add v4, v247, s[8:9] offset:2048
	global_atomic_add v4, v247, s[8:9] offset:2304
	global_atomic_add v4, v247, s[8:9] offset:2560
	global_atomic_add v4, v247, s[8:9] offset:2816
	global_atomic_add v4, v247, s[8:9] offset:3072
	global_atomic_add v4, v247, s[8:9] offset:3328
	global_atomic_add v4, v247, s[8:9] offset:3584
	global_atomic_add v4, v247, s[8:9] offset:3840
.Lxg_5:
	s_and_saveexec_b64 s[14:15], vcc
	s_cbranch_execz .LBB0_415
	global_load_dword v2, v1, s[12:13] sc1
	s_mov_b64 s[20:21], 0
	s_waitcnt vmcnt(0)
	v_cmp_eq_u32_e32 vcc, v2, v0
	s_and_saveexec_b64 s[18:19], vcc
	s_cbranch_execz .LBB0_414
	s_add_u32 s16, s8, 0xf101200
	s_addc_u32 s17, s9, 0
	s_mov_b32 s28, 1
	s_mov_b64 s[8:9], 0
	s_branch .LBB0_407

.LBB0_417:
	s_or_b64 exec, exec, s[8:9]
	s_mov_b64 s[8:9], exec
	v_mbcnt_lo_u32_b32 v0, s8, 0
	v_mbcnt_hi_u32_b32 v0, s9, v0
	v_cmp_eq_u32_e32 vcc, 0, v0
	s_waitcnt vmcnt(0)
	buffer_inv sc1
	s_and_saveexec_b64 s[12:13], vcc
	s_cbranch_execz .LBB0_419
	s_bcnt1_i32_b64 s8, s[8:9]
	v_mov_b32_e32 v0, s8
	v_mov_b32_e32 v2, 0x2000
.LBB0_419:
	s_or_b64 exec, exec, s[12:13]
	s_waitcnt vmcnt(0)

.LBB0_508:
	s_or_b64 exec, exec, s[16:17]
	s_waitcnt vmcnt(0)
	v_readfirstlane_b32 s14, v3
	v_sub_u32_e32 v4, 0, v2
	s_mov_b64 s[18:19], -1
	v_add_u32_e32 v3, s14, v0
	v_cvt_f32_u32_e32 v0, v2
	s_add_u32 s14, s10, 0xf104500
	s_addc_u32 s15, s11, 0
	v_rcp_iflag_f32_e32 v0, v0
	s_nop 0
	v_mul_f32_e32 v0, 0x4f7ffffe, v0
	v_cvt_u32_f32_e32 v0, v0
	v_mul_lo_u32 v4, v4, v0
	v_mul_hi_u32 v4, v0, v4
	v_add_u32_e32 v0, v0, v4
	v_mul_hi_u32 v0, v3, v0
	v_mul_lo_u32 v4, v0, v2
	v_sub_u32_e32 v4, v3, v4
	v_cmp_ge_u32_e32 vcc, v4, v2
	v_add_u32_e32 v5, 1, v0
	v_add_u32_e32 v3, 1, v3
	v_cndmask_b32_e32 v0, v0, v5, vcc
	v_sub_u32_e32 v5, v4, v2
	v_cndmask_b32_e32 v4, v4, v5, vcc
	v_cmp_ge_u32_e32 vcc, v4, v2
	v_add_u32_e32 v4, 1, v0
	s_nop 0
	v_cndmask_b32_e32 v0, v0, v4, vcc
	v_mul_lo_u32 v4, v2, v0
	v_add_u32_e32 v2, v4, v2
	v_cmp_ne_u32_e32 vcc, v3, v2
	v_mov_b64_e32 v[2:3], s[14:15]
	s_cbranch_vccnz .Lxg_4
	v_mov_b32_e32 v4, 0xf103400
	global_atomic_add v4, v247, s[10:11] offset:0
	global_atomic_add v4, v247, s[10:11] offset:256
	global_atomic_add v4, v247, s[10:11] offset:512
	global_atomic_add v4, v247, s[10:11] offset:768
	global_atomic_add v4, v247, s[10:11] offset:1024
	global_atomic_add v4, v247, s[10:11] offset:1280
	global_atomic_add v4, v247, s[10:11] offset:1536
	global_atomic_add v4, v247, s[10:11] offset:1792
	global_atomic_add v4, v247, s[10:11] offset:2048
	global_atomic_add v4, v247, s[10:11] offset:2304
	global_atomic_add v4, v247, s[10:11] offset:2560
	global_atomic_add v4, v247, s[10:11] offset:2816
	global_atomic_add v4, v247, s[10:11] offset:3072
	global_atomic_add v4, v247, s[10:11] offset:3328
	global_atomic_add v4, v247, s[10:11] offset:3584
	global_atomic_add v4, v247, s[10:11] offset:3840
.Lxg_4:
	s_and_saveexec_b64 s[16:17], vcc
	s_cbranch_execz .LBB0_520
	global_load_dword v2, v1, s[14:15] sc1
	s_mov_b64 s[22:23], 0
	s_waitcnt vmcnt(0)
	v_cmp_eq_u32_e32 vcc, v2, v0
	s_and_saveexec_b64 s[20:21], vcc
	s_cbranch_execz .LBB0_519
	s_add_u32 s18, s10, 0xf101200
	s_addc_u32 s19, s11, 0
	s_mov_b32 s30, 1
	s_mov_b64 s[10:11], 0
	s_branch .LBB0_512

.LBB0_522:
	s_or_b64 exec, exec, s[10:11]
	s_mov_b64 s[10:11], exec
	v_mbcnt_lo_u32_b32 v0, s10, 0
	v_mbcnt_hi_u32_b32 v0, s11, v0
	v_cmp_eq_u32_e32 vcc, 0, v0
	s_waitcnt vmcnt(0)
	buffer_inv sc1
	s_and_saveexec_b64 s[14:15], vcc
	s_cbranch_execz .LBB0_524
	s_bcnt1_i32_b64 s10, s[10:11]
	v_mov_b32_e32 v0, s10
	v_mov_b32_e32 v2, 0x2000
.LBB0_524:
	s_or_b64 exec, exec, s[14:15]
	s_waitcnt vmcnt(0)

.LBB0_645:
	s_or_b64 exec, exec, s[18:19]
	s_waitcnt vmcnt(0)
	v_readfirstlane_b32 s4, v3
	v_sub_u32_e32 v4, 0, v2
	s_add_u32 s16, s12, 0xf104500
	v_add_u32_e32 v3, s4, v0
	v_cvt_f32_u32_e32 v0, v2
	s_addc_u32 s17, s13, 0
	s_mov_b64 s[20:21], -1
	v_rcp_iflag_f32_e32 v0, v0
	s_nop 0
	v_mul_f32_e32 v0, 0x4f7ffffe, v0
	v_cvt_u32_f32_e32 v0, v0
	v_mul_lo_u32 v4, v4, v0
	v_mul_hi_u32 v4, v0, v4
	v_add_u32_e32 v0, v0, v4
	v_mul_hi_u32 v0, v3, v0
	v_mul_lo_u32 v4, v0, v2
	v_sub_u32_e32 v4, v3, v4
	v_cmp_ge_u32_e32 vcc, v4, v2
	v_add_u32_e32 v5, 1, v0
	v_add_u32_e32 v3, 1, v3
	v_cndmask_b32_e32 v0, v0, v5, vcc
	v_sub_u32_e32 v5, v4, v2
	v_cndmask_b32_e32 v4, v4, v5, vcc
	v_cmp_ge_u32_e32 vcc, v4, v2
	v_add_u32_e32 v4, 1, v0
	s_nop 0
	v_cndmask_b32_e32 v0, v0, v4, vcc
	v_mul_lo_u32 v4, v2, v0
	v_add_u32_e32 v2, v4, v2
	v_cmp_ne_u32_e32 vcc, v3, v2
	v_mov_b64_e32 v[2:3], s[16:17]
	s_cbranch_vccnz .Lxg_3
	v_mov_b32_e32 v4, 0xf103400
	global_atomic_add v4, v247, s[12:13] offset:0
	global_atomic_add v4, v247, s[12:13] offset:256
	global_atomic_add v4, v247, s[12:13] offset:512
	global_atomic_add v4, v247, s[12:13] offset:768
	global_atomic_add v4, v247, s[12:13] offset:1024
	global_atomic_add v4, v247, s[12:13] offset:1280
	global_atomic_add v4, v247, s[12:13] offset:1536
	global_atomic_add v4, v247, s[12:13] offset:1792
	global_atomic_add v4, v247, s[12:13] offset:2048
	global_atomic_add v4, v247, s[12:13] offset:2304
	global_atomic_add v4, v247, s[12:13] offset:2560
	global_atomic_add v4, v247, s[12:13] offset:2816
	global_atomic_add v4, v247, s[12:13] offset:3072
	global_atomic_add v4, v247, s[12:13] offset:3328
	global_atomic_add v4, v247, s[12:13] offset:3584
	global_atomic_add v4, v247, s[12:13] offset:3840
.Lxg_3:
	s_and_saveexec_b64 s[18:19], vcc
	s_cbranch_execz .LBB0_657
	global_load_dword v2, v1, s[16:17] sc1
	s_mov_b64 s[24:25], 0
	s_waitcnt vmcnt(0)
	v_cmp_eq_u32_e32 vcc, v2, v0
	s_and_saveexec_b64 s[22:23], vcc
	s_cbranch_execz .LBB0_656
	s_add_u32 s20, s12, 0xf101200
	s_addc_u32 s21, s13, 0
	s_mov_b32 s34, 1
	s_mov_b64 s[12:13], 0
	s_branch .LBB0_649

.LBB0_659:
	s_or_b64 exec, exec, s[12:13]
	s_mov_b64 s[12:13], exec
	v_mbcnt_lo_u32_b32 v0, s12, 0
	v_mbcnt_hi_u32_b32 v0, s13, v0
	v_cmp_eq_u32_e32 vcc, 0, v0
	s_waitcnt vmcnt(0)
	buffer_inv sc1
	s_and_saveexec_b64 s[16:17], vcc
	s_cbranch_execz .LBB0_661
	s_bcnt1_i32_b64 s4, s[12:13]
	v_mov_b32_e32 v0, s4
	v_mov_b32_e32 v2, 0x2000
.LBB0_661:
	s_or_b64 exec, exec, s[16:17]
	s_waitcnt vmcnt(0)

.LBB0_743:
	s_or_b64 exec, exec, s[16:17]
	s_waitcnt vmcnt(0)
	v_readfirstlane_b32 s4, v3
	v_sub_u32_e32 v4, 0, v2
	s_add_u32 s14, s10, 0xf104500
	v_add_u32_e32 v3, s4, v0
	v_cvt_f32_u32_e32 v0, v2
	s_addc_u32 s15, s11, 0
	s_mov_b64 s[18:19], -1
	v_rcp_iflag_f32_e32 v0, v0
	s_nop 0
	v_mul_f32_e32 v0, 0x4f7ffffe, v0
	v_cvt_u32_f32_e32 v0, v0
	v_mul_lo_u32 v4, v4, v0
	v_mul_hi_u32 v4, v0, v4
	v_add_u32_e32 v0, v0, v4
	v_mul_hi_u32 v0, v3, v0
	v_mul_lo_u32 v4, v0, v2
	v_sub_u32_e32 v4, v3, v4
	v_cmp_ge_u32_e32 vcc, v4, v2
	v_add_u32_e32 v5, 1, v0
	v_add_u32_e32 v3, 1, v3
	v_cndmask_b32_e32 v0, v0, v5, vcc
	v_sub_u32_e32 v5, v4, v2
	v_cndmask_b32_e32 v4, v4, v5, vcc
	v_cmp_ge_u32_e32 vcc, v4, v2
	v_add_u32_e32 v4, 1, v0
	s_nop 0
	v_cndmask_b32_e32 v0, v0, v4, vcc
	v_mul_lo_u32 v4, v2, v0
	v_add_u32_e32 v2, v4, v2
	v_cmp_ne_u32_e32 vcc, v3, v2
	v_mov_b64_e32 v[2:3], s[14:15]
	s_cbranch_vccnz .Lxg_2
	v_mov_b32_e32 v4, 0xf103400
	global_atomic_add v4, v247, s[10:11] offset:0
	global_atomic_add v4, v247, s[10:11] offset:256
	global_atomic_add v4, v247, s[10:11] offset:512
	global_atomic_add v4, v247, s[10:11] offset:768
	global_atomic_add v4, v247, s[10:11] offset:1024
	global_atomic_add v4, v247, s[10:11] offset:1280
	global_atomic_add v4, v247, s[10:11] offset:1536
	global_atomic_add v4, v247, s[10:11] offset:1792
	global_atomic_add v4, v247, s[10:11] offset:2048
	global_atomic_add v4, v247, s[10:11] offset:2304
	global_atomic_add v4, v247, s[10:11] offset:2560
	global_atomic_add v4, v247, s[10:11] offset:2816
	global_atomic_add v4, v247, s[10:11] offset:3072
	global_atomic_add v4, v247, s[10:11] offset:3328
	global_atomic_add v4, v247, s[10:11] offset:3584
	global_atomic_add v4, v247, s[10:11] offset:3840

.LBB0_757:
	s_or_b64 exec, exec, s[10:11]
	s_mov_b64 s[10:11], exec
	v_mbcnt_lo_u32_b32 v0, s10, 0
	v_mbcnt_hi_u32_b32 v0, s11, v0
	v_cmp_eq_u32_e32 vcc, 0, v0
	s_waitcnt vmcnt(0)
	buffer_inv sc1
	s_and_saveexec_b64 s[14:15], vcc
	s_cbranch_execz .LBB0_759
	s_bcnt1_i32_b64 s4, s[10:11]
	v_mov_b32_e32 v0, s4
	v_mov_b32_e32 v2, 0x2000
.LBB0_759:
	s_or_b64 exec, exec, s[14:15]
	s_waitcnt vmcnt(0)

.LBB0_845:
	s_or_b64 exec, exec, s[12:13]
	s_mov_b64 s[12:13], exec
	v_mbcnt_lo_u32_b32 v0, s12, 0
	v_mbcnt_hi_u32_b32 v0, s13, v0
	v_cmp_eq_u32_e32 vcc, 0, v0
	s_waitcnt vmcnt(0)
	buffer_inv sc1
	s_and_saveexec_b64 s[16:17], vcc
	s_cbranch_execz .LBB0_847
	s_bcnt1_i32_b64 s4, s[12:13]
	v_mov_b32_e32 v0, s4
	v_mov_b32_e32 v2, 0x2000
.LBB0_847:
	s_or_b64 exec, exec, s[16:17]
	s_waitcnt vmcnt(0)

.LBB0_996:
	s_or_b64 exec, exec, s[14:15]
	s_waitcnt vmcnt(0)
	v_readfirstlane_b32 s4, v3
	v_sub_u32_e32 v4, 0, v2
	s_add_u32 s12, s8, 0xf104500
	v_add_u32_e32 v3, s4, v0
	v_cvt_f32_u32_e32 v0, v2
	s_addc_u32 s13, s9, 0
	s_mov_b64 s[16:17], -1
	v_rcp_iflag_f32_e32 v0, v0
	s_nop 0
	v_mul_f32_e32 v0, 0x4f7ffffe, v0
	v_cvt_u32_f32_e32 v0, v0
	v_mul_lo_u32 v4, v4, v0
	v_mul_hi_u32 v4, v0, v4
	v_add_u32_e32 v0, v0, v4
	v_mul_hi_u32 v0, v3, v0
	v_mul_lo_u32 v4, v0, v2
	v_sub_u32_e32 v4, v3, v4
	v_cmp_ge_u32_e32 vcc, v4, v2
	v_add_u32_e32 v5, 1, v0
	v_add_u32_e32 v3, 1, v3
	v_cndmask_b32_e32 v0, v0, v5, vcc
	v_sub_u32_e32 v5, v4, v2
	v_cndmask_b32_e32 v4, v4, v5, vcc
	v_cmp_ge_u32_e32 vcc, v4, v2
	v_add_u32_e32 v4, 1, v0
	s_nop 0
	v_cndmask_b32_e32 v0, v0, v4, vcc
	v_mul_lo_u32 v4, v2, v0
	v_add_u32_e32 v2, v4, v2
	v_cmp_ne_u32_e32 vcc, v3, v2
	v_mov_b64_e32 v[2:3], s[12:13]
	s_cbranch_vccnz .Lxg_0
	v_mov_b32_e32 v4, 0xf103400
	global_atomic_add v4, v247, s[8:9] offset:0
	global_atomic_add v4, v247, s[8:9] offset:256
	global_atomic_add v4, v247, s[8:9] offset:512
	global_atomic_add v4, v247, s[8:9] offset:768
	global_atomic_add v4, v247, s[8:9] offset:1024
	global_atomic_add v4, v247, s[8:9] offset:1280
	global_atomic_add v4, v247, s[8:9] offset:1536
	global_atomic_add v4, v247, s[8:9] offset:1792
	global_atomic_add v4, v247, s[8:9] offset:2048
	global_atomic_add v4, v247, s[8:9] offset:2304
	global_atomic_add v4, v247, s[8:9] offset:2560
	global_atomic_add v4, v247, s[8:9] offset:2816
	global_atomic_add v4, v247, s[8:9] offset:3072
	global_atomic_add v4, v247, s[8:9] offset:3328
	global_atomic_add v4, v247, s[8:9] offset:3584
	global_atomic_add v4, v247, s[8:9] offset:3840

.LBB0_1011:
	s_bcnt1_i32_b64 s4, s[8:9]
	v_mov_b32_e32 v0, s4
	v_mov_b32_e32 v2, 0x2000
	s_getpc_b64 s[98:99]
